# gemm K-loops: B-fragment LDS address adds hoisted out of the loop into four loop-invariant VGPRs (no VALU left in the loading wave's segments); on top of v95
# baseline (speedup 1.0000x reference)
; #define PG8_STAGE(bufoff, gbase, voff) do { _Pragma("unroll") for (int _i = 0; _i < 2; ++_i) \
;         __builtin_amdgcn_global_load_lds((const unsigned*)((const char*)(gbase) + (voff)[_i]), (PG8_LAS unsigned*)(lds + (bufoff) + ldsw + _i * 8192), 16, 0, 0); } while (0)
; #define PG8_LDA(dst, b, h) do { _Pragma("unroll") for (int m = 0; m < 4; ++m) _Pragma("unroll") for (int k = 0; k < 2; ++k) dst[m][k] = *(const PG8_LAS bf16x8*)(lds + PG8_SA(b, h) + aoff + m * 2048 + k * 1024); } while (0)
; #define PG8_LDB(dst, b, h) do { _Pragma("unroll") for (int n = 0; n < 2; ++n) _Pragma("unroll") for (int k = 0; k < 2; ++k) dst[n][k] = *(const PG8_LAS bf16x8*)(lds + PG8_SB(b, h) + boff + n * 2048 + k * 1024); } while (0)
; #define PG8_SCHED __builtin_amdgcn_sched_barrier(0)
; template <class Epi, class Sched, bool ALIGN_EPI = false, bool SP2 = false>
; __device__ __forceinline__ void gemm_phase(PG8_LAS unsigned char* lds, const Gemm g, const Sched& S, const Epi& E) {
;     ...
;         const char* nA = has_next ? (const char*)g.A + (size_t)nxt.pm * tstep : cA; const char* nB = has_next ? (const char*)g.Bt + (size_t)nxt.pn * tstep : cB;
;         for (int t = 0; t < nt; t += 2) {
;             const bool last = (t == nt - 2);
;             const char* a1 = cA + (size_t)(t + 1) * kstep;
;             const char* a2 = last ? nA : cA + (size_t)(t + 2) * kstep; const char* b2 = last ? nB : cB + (size_t)(t + 2) * kstep;
;             const char* a3 = a2 + kstep; const char* b3 = b2 + kstep;
;             if (last && has_next) S.a_ready(nxt);
;             if constexpr (SP2) {
;             PG8_LDB(B0, 0, 0); PG8_LDB(B1, 0, 1); PG8_SCHED; PG8_LDA(At, 0, 0); PG8_STAGE(PG8_SA(1, 1), a1 + hstep, voffA);
;     ...
;         for (int a = 0; a < 2; ++a)
; #pragma unroll
;             for (int b = 0; b < 2; ++b)
; #pragma unroll
;                 for (int m = 0; m < 4; ++m)
; #pragma unroll
;                     for (int n = 0; n < 2; ++n) acc[a][b][m][n] = (f32x4){0.f, 0.f, 0.f, 0.f};
.LBB0_229:
	s_ashr_i32 s1, s0, 31
	s_lshl_b64 s[14:15], s[0:1], 19
	s_add_u32 s50, s77, s14
	s_addc_u32 s51, s78, s15
	s_and_b64 s[14:15], s[46:47], exec
	s_cselect_b32 s1, s51, s65
	s_cselect_b32 s14, s50, s64
	s_ashr_i32 s35, s34, 31
	s_lshl_b64 s[28:29], s[34:35], 19
	s_add_u32 s60, s79, s28
	s_addc_u32 s61, s80, s29
	s_and_b64 s[28:29], s[46:47], exec
	s_cselect_b32 s15, s61, s63
	s_cselect_b32 s20, s60, s62
	s_add_u32 s28, s62, 0x100
	s_addc_u32 s29, s63, 0
	s_add_u32 s62, s64, 0x40080
	v_mov_b32_e32 v2, 0
	s_addc_u32 s63, s65, 0
	s_mov_b32 s33, -2
	v_mov_b32_e32 v3, v2
	v_mov_b32_e32 v4, v2
	v_mov_b32_e32 v5, v2
	v_mov_b32_e32 v6, v2
	v_mov_b32_e32 v7, v2
	v_mov_b32_e32 v8, v2
	v_mov_b32_e32 v9, v2
	v_mov_b32_e32 v34, v2
	v_mov_b32_e32 v35, v2
	v_mov_b32_e32 v36, v2
	v_mov_b32_e32 v37, v2
	v_mov_b32_e32 v38, v2
	v_mov_b32_e32 v39, v2
	v_mov_b32_e32 v40, v2
	v_mov_b32_e32 v41, v2
	v_mov_b32_e32 v66, v2
	v_mov_b32_e32 v67, v2
	v_mov_b32_e32 v68, v2
	v_mov_b32_e32 v69, v2
	v_mov_b32_e32 v70, v2
	v_mov_b32_e32 v71, v2
	v_mov_b32_e32 v72, v2
	v_mov_b32_e32 v73, v2
	v_mov_b32_e32 v98, v2
	v_mov_b32_e32 v99, v2
	v_mov_b32_e32 v100, v2
	v_mov_b32_e32 v101, v2
	v_mov_b32_e32 v102, v2
	v_mov_b32_e32 v103, v2
	v_mov_b32_e32 v104, v2
	v_mov_b32_e32 v105, v2
	v_mov_b32_e32 v10, v2
	v_mov_b32_e32 v11, v2
	v_mov_b32_e32 v12, v2
	v_mov_b32_e32 v13, v2
	v_mov_b32_e32 v14, v2
	v_mov_b32_e32 v15, v2
	v_mov_b32_e32 v16, v2
	v_mov_b32_e32 v17, v2
	v_mov_b32_e32 v42, v2
	v_mov_b32_e32 v43, v2
	v_mov_b32_e32 v44, v2
	v_mov_b32_e32 v45, v2
	v_mov_b32_e32 v46, v2
	v_mov_b32_e32 v47, v2
	v_mov_b32_e32 v48, v2
	v_mov_b32_e32 v49, v2
	v_mov_b32_e32 v74, v2
	v_mov_b32_e32 v75, v2
	v_mov_b32_e32 v76, v2
	v_mov_b32_e32 v77, v2
	v_mov_b32_e32 v78, v2
	v_mov_b32_e32 v79, v2
	v_mov_b32_e32 v80, v2
	v_mov_b32_e32 v81, v2
	v_mov_b32_e32 v106, v2
	v_mov_b32_e32 v107, v2
	v_mov_b32_e32 v108, v2
	v_mov_b32_e32 v109, v2
	v_mov_b32_e32 v110, v2
	v_mov_b32_e32 v111, v2
	v_mov_b32_e32 v112, v2
	v_mov_b32_e32 v113, v2
	v_mov_b32_e32 v18, v2
	v_mov_b32_e32 v19, v2
	v_mov_b32_e32 v20, v2
	v_mov_b32_e32 v21, v2
	v_mov_b32_e32 v22, v2
	v_mov_b32_e32 v23, v2
	v_mov_b32_e32 v24, v2
	v_mov_b32_e32 v25, v2
	v_mov_b32_e32 v50, v2
	v_mov_b32_e32 v51, v2
	v_mov_b32_e32 v52, v2
	v_mov_b32_e32 v53, v2
	v_mov_b32_e32 v54, v2
	v_mov_b32_e32 v55, v2
	v_mov_b32_e32 v56, v2
	v_mov_b32_e32 v57, v2
	v_mov_b32_e32 v82, v2
	v_mov_b32_e32 v83, v2
	v_mov_b32_e32 v84, v2
	v_mov_b32_e32 v85, v2
	v_mov_b32_e32 v86, v2
	v_mov_b32_e32 v87, v2
	v_mov_b32_e32 v88, v2
	v_mov_b32_e32 v89, v2
	v_mov_b32_e32 v114, v2
	v_mov_b32_e32 v115, v2
	v_mov_b32_e32 v116, v2
	v_mov_b32_e32 v117, v2
	v_mov_b32_e32 v118, v2
	v_mov_b32_e32 v119, v2
	v_mov_b32_e32 v120, v2
	v_mov_b32_e32 v121, v2
	v_mov_b32_e32 v26, v2
	v_mov_b32_e32 v27, v2
	v_mov_b32_e32 v28, v2
	v_mov_b32_e32 v29, v2
	v_mov_b32_e32 v30, v2
	v_mov_b32_e32 v31, v2
	v_mov_b32_e32 v32, v2
	v_mov_b32_e32 v33, v2
	v_mov_b32_e32 v58, v2
	v_mov_b32_e32 v59, v2
	v_mov_b32_e32 v60, v2
	v_mov_b32_e32 v61, v2
	v_mov_b32_e32 v62, v2
	v_mov_b32_e32 v63, v2
	v_mov_b32_e32 v64, v2
	v_mov_b32_e32 v65, v2
	v_mov_b32_e32 v90, v2
	v_mov_b32_e32 v91, v2
	v_mov_b32_e32 v92, v2
	v_mov_b32_e32 v93, v2
	v_mov_b32_e32 v94, v2
	v_mov_b32_e32 v95, v2
	v_mov_b32_e32 v96, v2
	v_mov_b32_e32 v97, v2
	v_mov_b32_e32 v122, v2
	v_mov_b32_e32 v123, v2
	v_mov_b32_e32 v124, v2
	v_mov_b32_e32 v125, v2
	v_mov_b32_e32 v126, v2
	v_mov_b32_e32 v127, v2
	v_mov_b32_e32 v128, v2
	v_mov_b32_e32 v129, v2
	v_add_u32_e32 v249, 0x10000, v185
	v_add_u32_e32 v250, 0x14000, v185
	v_add_u32_e32 v251, 0x18000, v185
	v_add_u32_e32 v252, 0x1c000, v185
.LBB0_230:
	s_add_u32 s35, s62, 0xfffc0080
	s_addc_u32 s64, s63, -1
	s_add_i32 s68, 0, 0x10000
	s_cmp_eq_u32 s33, 12
	s_cselect_b32 s67, s1, s64
	s_cselect_b32 s66, s14, s35
	s_cselect_b32 s65, s15, s29
	s_cselect_b32 s64, s20, s28
	s_add_i32 s35, 0, 0x14000
	ds_read_b128 v[130:133], v249
	ds_read_b128 v[134:137], v249 offset:1024
	ds_read_b128 v[138:141], v249 offset:2048
	ds_read_b128 v[142:145], v249 offset:3072
	ds_read_b128 v[146:149], v250
	ds_read_b128 v[150:153], v250 offset:1024
	ds_read_b128 v[154:157], v250 offset:2048
	ds_read_b128 v[158:161], v250 offset:3072
	s_add_i32 m0, s82, 0xc000
	ds_read_b128 v[162:165], v187
	ds_read_b128 v[166:169], v187 offset:1024
	ds_read_b128 v[170:173], v187 offset:2048
	ds_read_b128 v[174:177], v187 offset:3072
	ds_read_b128 v[210:213], v187 offset:4096
	ds_read_b128 v[214:217], v187 offset:5120
	ds_read_b128 v[228:231], v187 offset:6144
	ds_read_b128 v[232:235], v187 offset:7168
	global_load_lds_dwordx4 v208, s[62:63]
	s_add_i32 m0, s82, 0xe000
	s_nop 0
	global_load_lds_dwordx4 v206, s[62:63]
	s_waitcnt vmcnt(8)
	s_waitcnt lgkmcnt(0)
	s_barrier
; #define PG8_STAGE(bufoff, gbase, voff) do { _Pragma("unroll") for (int _i = 0; _i < 2; ++_i) \
;         __builtin_amdgcn_global_load_lds((const unsigned*)((const char*)(gbase) + (voff)[_i]), (PG8_LAS unsigned*)(lds + (bufoff) + ldsw + _i * 8192), 16, 0, 0); } while (0)
; #define PG8_LDA(dst, b, h) do { _Pragma("unroll") for (int m = 0; m < 4; ++m) _Pragma("unroll") for (int k = 0; k < 2; ++k) dst[m][k] = *(const PG8_LAS bf16x8*)(lds + PG8_SA(b, h) + aoff + m * 2048 + k * 1024); } while (0)
; #define PG8_MMA(ai, bj, At, Bt) do { __builtin_amdgcn_s_setprio(1); _Pragma("unroll") for (int m = 0; m < 4; ++m) _Pragma("unroll") for (int n = 0; n < 2; ++n) _Pragma("unroll") for (int k = 0; k < 2; ++k) \
;         acc[ai][bj][m][n] = __builtin_amdgcn_mfma_f32_16x16x32_bf16(Bt[n][k], At[m][k], acc[ai][bj][m][n], 0, 0, 0); __builtin_amdgcn_s_setprio(0); } while (0)
; #define PG8_WAIT_V(n) asm volatile("s_waitcnt vmcnt(" #n ")" ::: "memory")
; #define PG8_WAIT_L(n) asm volatile("s_waitcnt lgkmcnt(" #n ")" ::: "memory")
; #define PG8_BAR __builtin_amdgcn_s_barrier()
; #define PG8_SCHED __builtin_amdgcn_sched_barrier(0)
; template <class Epi, class Sched, bool ALIGN_EPI = false, bool SP2 = false>
; __device__ __forceinline__ void gemm_phase(PG8_LAS unsigned char* lds, const Gemm g, const Sched& S, const Epi& E) {
;     ...
;             PG8_WAIT_V(8); PG8_WAIT_L(0); PG8_BAR; PG8_MMA(0, 0, At, B0); PG8_MMA(0, 1, At, B1); PG8_BAR; PG8_SCHED;
;             PG8_LDA(At, 0, 1); PG8_STAGE(PG8_SB(0, 0), b2, voffB); PG8_STAGE(PG8_SB(0, 1), b2 + hstep, voffB); PG8_STAGE(PG8_SA(0, 0), a2, voffA);
;             PG8_WAIT_V(8); PG8_WAIT_L(0); PG8_BAR; PG8_MMA(1, 0, At, B0); PG8_MMA(1, 1, At, B1); PG8_BAR; PG8_SCHED;
	s_setprio 1
	s_waitcnt lgkmcnt(0)
	v_mfma_f32_16x16x32_bf16 v[126:129], v[130:133], v[162:165], v[126:129]
	v_mfma_f32_16x16x32_bf16 v[122:125], v[138:141], v[162:165], v[122:125]
	v_mfma_f32_16x16x32_bf16 v[94:97], v[130:133], v[170:173], v[94:97]
	v_mfma_f32_16x16x32_bf16 v[90:93], v[138:141], v[170:173], v[90:93]
	v_mfma_f32_16x16x32_bf16 v[62:65], v[130:133], v[210:213], v[62:65]
	v_mfma_f32_16x16x32_bf16 v[58:61], v[138:141], v[210:213], v[58:61]
	v_mfma_f32_16x16x32_bf16 v[30:33], v[130:133], v[228:231], v[30:33]
	v_mfma_f32_16x16x32_bf16 v[26:29], v[138:141], v[228:231], v[26:29]
	v_mfma_f32_16x16x32_bf16 v[126:129], v[134:137], v[166:169], v[126:129]
	v_mfma_f32_16x16x32_bf16 v[122:125], v[142:145], v[166:169], v[122:125]
	v_mfma_f32_16x16x32_bf16 v[94:97], v[134:137], v[174:177], v[94:97]
	v_mfma_f32_16x16x32_bf16 v[90:93], v[142:145], v[174:177], v[90:93]
	v_mfma_f32_16x16x32_bf16 v[62:65], v[134:137], v[214:217], v[62:65]
	v_mfma_f32_16x16x32_bf16 v[58:61], v[142:145], v[214:217], v[58:61]
	v_mfma_f32_16x16x32_bf16 v[30:33], v[134:137], v[232:235], v[30:33]
	v_mfma_f32_16x16x32_bf16 v[26:29], v[142:145], v[232:235], v[26:29]
	s_setprio 0
	s_setprio 1
	v_mfma_f32_16x16x32_bf16 v[118:121], v[146:149], v[162:165], v[118:121]
	v_mfma_f32_16x16x32_bf16 v[114:117], v[154:157], v[162:165], v[114:117]
	v_mfma_f32_16x16x32_bf16 v[86:89], v[146:149], v[170:173], v[86:89]
	v_mfma_f32_16x16x32_bf16 v[82:85], v[154:157], v[170:173], v[82:85]
	v_mfma_f32_16x16x32_bf16 v[54:57], v[146:149], v[210:213], v[54:57]
	v_mfma_f32_16x16x32_bf16 v[50:53], v[154:157], v[210:213], v[50:53]
	v_mfma_f32_16x16x32_bf16 v[22:25], v[146:149], v[228:231], v[22:25]
	v_mfma_f32_16x16x32_bf16 v[18:21], v[154:157], v[228:231], v[18:21]
	v_mfma_f32_16x16x32_bf16 v[118:121], v[150:153], v[166:169], v[118:121]
	v_mfma_f32_16x16x32_bf16 v[114:117], v[158:161], v[166:169], v[114:117]
	v_mfma_f32_16x16x32_bf16 v[86:89], v[150:153], v[174:177], v[86:89]
	v_mfma_f32_16x16x32_bf16 v[82:85], v[158:161], v[174:177], v[82:85]
	v_mfma_f32_16x16x32_bf16 v[54:57], v[150:153], v[214:217], v[54:57]
	v_mfma_f32_16x16x32_bf16 v[50:53], v[158:161], v[214:217], v[50:53]
	v_mfma_f32_16x16x32_bf16 v[22:25], v[150:153], v[232:235], v[22:25]
	v_mfma_f32_16x16x32_bf16 v[18:21], v[158:161], v[232:235], v[18:21]
	s_setprio 0
	s_barrier
	s_add_i32 s68, s68, s81
	s_mov_b32 m0, s68
	ds_read_b128 v[162:165], v187 offset:16384
	ds_read_b128 v[166:169], v187 offset:17408
	ds_read_b128 v[170:173], v187 offset:18432
	ds_read_b128 v[174:177], v187 offset:19456
	ds_read_b128 v[210:213], v187 offset:20480
	ds_read_b128 v[214:217], v187 offset:21504
	ds_read_b128 v[228:231], v187 offset:22528
	ds_read_b128 v[232:235], v187 offset:23552
	global_load_lds_dwordx4 v180, s[64:65]
	s_add_i32 m0, s68, 0x2000
	s_add_u32 s68, s64, 0x40000
	s_addc_u32 s69, s65, 0
	s_add_i32 s35, s35, s81
	global_load_lds_dwordx4 v178, s[64:65]
	s_mov_b32 m0, s35
	s_nop 0
	global_load_lds_dwordx4 v180, s[68:69]
	s_add_i32 m0, s35, 0x2000
	s_nop 0
	global_load_lds_dwordx4 v178, s[68:69]
	s_mov_b32 m0, s82
	s_nop 0
	global_load_lds_dwordx4 v180, s[66:67]
	s_mov_b32 m0, s83
	s_nop 0
	global_load_lds_dwordx4 v178, s[66:67]
	s_waitcnt vmcnt(8)
	s_waitcnt lgkmcnt(0)
	s_barrier
	s_setprio 1
	s_waitcnt lgkmcnt(0)
	v_mfma_f32_16x16x32_bf16 v[110:113], v[130:133], v[162:165], v[110:113]
	v_mfma_f32_16x16x32_bf16 v[106:109], v[138:141], v[162:165], v[106:109]
	v_mfma_f32_16x16x32_bf16 v[78:81], v[130:133], v[170:173], v[78:81]
	v_mfma_f32_16x16x32_bf16 v[74:77], v[138:141], v[170:173], v[74:77]
	v_mfma_f32_16x16x32_bf16 v[46:49], v[130:133], v[210:213], v[46:49]
	v_mfma_f32_16x16x32_bf16 v[42:45], v[138:141], v[210:213], v[42:45]
	v_mfma_f32_16x16x32_bf16 v[14:17], v[130:133], v[228:231], v[14:17]
	v_mfma_f32_16x16x32_bf16 v[10:13], v[138:141], v[228:231], v[10:13]
	v_mfma_f32_16x16x32_bf16 v[110:113], v[134:137], v[166:169], v[110:113]
	v_mfma_f32_16x16x32_bf16 v[106:109], v[142:145], v[166:169], v[106:109]
	v_mfma_f32_16x16x32_bf16 v[78:81], v[134:137], v[174:177], v[78:81]
	v_mfma_f32_16x16x32_bf16 v[74:77], v[142:145], v[174:177], v[74:77]
	v_mfma_f32_16x16x32_bf16 v[46:49], v[134:137], v[214:217], v[46:49]
	v_mfma_f32_16x16x32_bf16 v[42:45], v[142:145], v[214:217], v[42:45]
	v_mfma_f32_16x16x32_bf16 v[14:17], v[134:137], v[232:235], v[14:17]
	v_mfma_f32_16x16x32_bf16 v[10:13], v[142:145], v[232:235], v[10:13]
	s_setprio 0
	s_setprio 1
	v_mfma_f32_16x16x32_bf16 v[102:105], v[146:149], v[162:165], v[102:105]
	v_mfma_f32_16x16x32_bf16 v[98:101], v[154:157], v[162:165], v[98:101]
	v_mfma_f32_16x16x32_bf16 v[70:73], v[146:149], v[170:173], v[70:73]
	v_mfma_f32_16x16x32_bf16 v[66:69], v[154:157], v[170:173], v[66:69]
	v_mfma_f32_16x16x32_bf16 v[38:41], v[146:149], v[210:213], v[38:41]
	v_mfma_f32_16x16x32_bf16 v[34:37], v[154:157], v[210:213], v[34:37]
	v_mfma_f32_16x16x32_bf16 v[6:9], v[146:149], v[228:231], v[6:9]
	v_mfma_f32_16x16x32_bf16 v[2:5], v[154:157], v[228:231], v[2:5]
	v_mfma_f32_16x16x32_bf16 v[102:105], v[150:153], v[166:169], v[102:105]
	v_mfma_f32_16x16x32_bf16 v[98:101], v[158:161], v[166:169], v[98:101]
	v_mfma_f32_16x16x32_bf16 v[70:73], v[150:153], v[174:177], v[70:73]
	v_mfma_f32_16x16x32_bf16 v[66:69], v[158:161], v[174:177], v[66:69]
	v_mfma_f32_16x16x32_bf16 v[38:41], v[150:153], v[214:217], v[38:41]
	v_mfma_f32_16x16x32_bf16 v[34:37], v[158:161], v[214:217], v[34:37]
	v_mfma_f32_16x16x32_bf16 v[6:9], v[150:153], v[232:235], v[6:9]
	v_mfma_f32_16x16x32_bf16 v[2:5], v[158:161], v[232:235], v[2:5]
	s_setprio 0
	s_barrier
; #define PG8_STAGE(bufoff, gbase, voff) do { _Pragma("unroll") for (int _i = 0; _i < 2; ++_i) \
;         __builtin_amdgcn_global_load_lds((const unsigned*)((const char*)(gbase) + (voff)[_i]), (PG8_LAS unsigned*)(lds + (bufoff) + ldsw + _i * 8192), 16, 0, 0); } while (0)
; #define PG8_LDA(dst, b, h) do { _Pragma("unroll") for (int m = 0; m < 4; ++m) _Pragma("unroll") for (int k = 0; k < 2; ++k) dst[m][k] = *(const PG8_LAS bf16x8*)(lds + PG8_SA(b, h) + aoff + m * 2048 + k * 1024); } while (0)
; #define PG8_LDB(dst, b, h) do { _Pragma("unroll") for (int n = 0; n < 2; ++n) _Pragma("unroll") for (int k = 0; k < 2; ++k) dst[n][k] = *(const PG8_LAS bf16x8*)(lds + PG8_SB(b, h) + boff + n * 2048 + k * 1024); } while (0)
; #define PG8_MMA(ai, bj, At, Bt) do { __builtin_amdgcn_s_setprio(1); _Pragma("unroll") for (int m = 0; m < 4; ++m) _Pragma("unroll") for (int n = 0; n < 2; ++n) _Pragma("unroll") for (int k = 0; k < 2; ++k) \
;         acc[ai][bj][m][n] = __builtin_amdgcn_mfma_f32_16x16x32_bf16(Bt[n][k], At[m][k], acc[ai][bj][m][n], 0, 0, 0); __builtin_amdgcn_s_setprio(0); } while (0)
; #define PG8_WAIT_V(n) asm volatile("s_waitcnt vmcnt(" #n ")" ::: "memory")
; #define PG8_WAIT_L(n) asm volatile("s_waitcnt lgkmcnt(" #n ")" ::: "memory")
; #define PG8_BAR __builtin_amdgcn_s_barrier()
; #define PG8_SCHED __builtin_amdgcn_sched_barrier(0)
; template <class Epi, class Sched, bool ALIGN_EPI = false, bool SP2 = false>
; __device__ __forceinline__ void gemm_phase(PG8_LAS unsigned char* lds, const Gemm g, const Sched& S, const Epi& E) {
;     ...
;             PG8_LDB(B0, 1, 0); PG8_LDB(B1, 1, 1); PG8_SCHED; PG8_LDA(At, 1, 0); PG8_STAGE(PG8_SA(0, 1), a2 + hstep, voffA);
;             PG8_WAIT_V(8); PG8_WAIT_L(0); PG8_BAR; PG8_MMA(0, 0, At, B0); PG8_MMA(0, 1, At, B1); PG8_BAR; PG8_SCHED;
;             PG8_LDA(At, 1, 1); PG8_STAGE(PG8_SB(1, 0), b3, voffB); PG8_STAGE(PG8_SB(1, 1), b3 + hstep, voffB); PG8_STAGE(PG8_SA(1, 0), a3, voffA);
;             PG8_WAIT_V(8); PG8_WAIT_L(0); PG8_BAR; PG8_MMA(1, 0, At, B0); PG8_MMA(1, 1, At, B1); PG8_BAR; PG8_SCHED;
;     ...
;         if constexpr (ALIGN_EPI) { if (wr == 0) PG8_BAR; }
	s_add_i32 s35, 0, 0x18000
	s_add_i32 s68, 0, 0x1c000
	ds_read_b128 v[130:133], v251
	ds_read_b128 v[134:137], v251 offset:1024
	ds_read_b128 v[138:141], v251 offset:2048
	ds_read_b128 v[142:145], v251 offset:3072
	ds_read_b128 v[146:149], v252
	ds_read_b128 v[150:153], v252 offset:1024
	ds_read_b128 v[154:157], v252 offset:2048
	ds_read_b128 v[158:161], v252 offset:3072
	s_add_u32 s66, s66, 0x40000
	s_addc_u32 s67, s67, 0
	s_add_u32 s98, s66, 0xfffc0080
	s_addc_u32 s99, s67, -1
	s_mov_b32 m0, s84
	ds_read_b128 v[162:165], v187 offset:32768
	ds_read_b128 v[166:169], v187 offset:33792
	ds_read_b128 v[170:173], v187 offset:34816
	ds_read_b128 v[174:177], v187 offset:35840
	ds_read_b128 v[210:213], v187 offset:36864
	ds_read_b128 v[214:217], v187 offset:37888
	ds_read_b128 v[228:231], v187 offset:38912
	ds_read_b128 v[232:235], v187 offset:39936
	global_load_lds_dwordx4 v180, s[66:67]
	s_mov_b32 m0, s85
	s_nop 0
	global_load_lds_dwordx4 v178, s[66:67]
	s_waitcnt vmcnt(8)
	s_waitcnt lgkmcnt(0)
	s_barrier
	s_setprio 1
	s_waitcnt lgkmcnt(0)
	v_mfma_f32_16x16x32_bf16 v[126:129], v[130:133], v[162:165], v[126:129]
	v_mfma_f32_16x16x32_bf16 v[122:125], v[138:141], v[162:165], v[122:125]
	v_mfma_f32_16x16x32_bf16 v[94:97], v[130:133], v[170:173], v[94:97]
	v_mfma_f32_16x16x32_bf16 v[90:93], v[138:141], v[170:173], v[90:93]
	v_mfma_f32_16x16x32_bf16 v[62:65], v[130:133], v[210:213], v[62:65]
	v_mfma_f32_16x16x32_bf16 v[58:61], v[138:141], v[210:213], v[58:61]
	v_mfma_f32_16x16x32_bf16 v[30:33], v[130:133], v[228:231], v[30:33]
	v_mfma_f32_16x16x32_bf16 v[26:29], v[138:141], v[228:231], v[26:29]
	v_mfma_f32_16x16x32_bf16 v[126:129], v[134:137], v[166:169], v[126:129]
	v_mfma_f32_16x16x32_bf16 v[122:125], v[142:145], v[166:169], v[122:125]
	v_mfma_f32_16x16x32_bf16 v[94:97], v[134:137], v[174:177], v[94:97]
	v_mfma_f32_16x16x32_bf16 v[90:93], v[142:145], v[174:177], v[90:93]
	v_mfma_f32_16x16x32_bf16 v[62:65], v[134:137], v[214:217], v[62:65]
	v_mfma_f32_16x16x32_bf16 v[58:61], v[142:145], v[214:217], v[58:61]
	v_mfma_f32_16x16x32_bf16 v[30:33], v[134:137], v[232:235], v[30:33]
	v_mfma_f32_16x16x32_bf16 v[26:29], v[142:145], v[232:235], v[26:29]
	s_setprio 0
	s_setprio 1
	v_mfma_f32_16x16x32_bf16 v[118:121], v[146:149], v[162:165], v[118:121]
	v_mfma_f32_16x16x32_bf16 v[114:117], v[154:157], v[162:165], v[114:117]
	v_mfma_f32_16x16x32_bf16 v[86:89], v[146:149], v[170:173], v[86:89]
	v_mfma_f32_16x16x32_bf16 v[82:85], v[154:157], v[170:173], v[82:85]
	v_mfma_f32_16x16x32_bf16 v[54:57], v[146:149], v[210:213], v[54:57]
	v_mfma_f32_16x16x32_bf16 v[50:53], v[154:157], v[210:213], v[50:53]
	v_mfma_f32_16x16x32_bf16 v[22:25], v[146:149], v[228:231], v[22:25]
	v_mfma_f32_16x16x32_bf16 v[18:21], v[154:157], v[228:231], v[18:21]
	v_mfma_f32_16x16x32_bf16 v[118:121], v[150:153], v[166:169], v[118:121]
	v_mfma_f32_16x16x32_bf16 v[114:117], v[158:161], v[166:169], v[114:117]
	v_mfma_f32_16x16x32_bf16 v[86:89], v[150:153], v[174:177], v[86:89]
	v_mfma_f32_16x16x32_bf16 v[82:85], v[158:161], v[174:177], v[82:85]
	v_mfma_f32_16x16x32_bf16 v[54:57], v[150:153], v[214:217], v[54:57]
	v_mfma_f32_16x16x32_bf16 v[50:53], v[158:161], v[214:217], v[50:53]
	v_mfma_f32_16x16x32_bf16 v[22:25], v[150:153], v[232:235], v[22:25]
	v_mfma_f32_16x16x32_bf16 v[18:21], v[158:161], v[232:235], v[18:21]
	s_setprio 0
	s_barrier
	s_add_i32 s35, s35, s81
	s_add_u32 s64, s64, s38
	s_addc_u32 s65, s65, s39
	s_mov_b32 m0, s35
	ds_read_b128 v[162:165], v187 offset:49152
	ds_read_b128 v[166:169], v187 offset:50176
	ds_read_b128 v[170:173], v187 offset:51200
	ds_read_b128 v[174:177], v187 offset:52224
	ds_read_b128 v[210:213], v187 offset:53248
	ds_read_b128 v[214:217], v187 offset:54272
	ds_read_b128 v[228:231], v187 offset:55296
	ds_read_b128 v[232:235], v187 offset:56320
	global_load_lds_dwordx4 v180, s[64:65]
	s_add_i32 m0, s35, 0x2000
	s_add_i32 s35, s68, s81
	global_load_lds_dwordx4 v178, s[64:65]
	s_add_u32 s64, s64, 0x40000
	s_addc_u32 s65, s65, 0
	s_mov_b32 m0, s35
	s_nop 0
	global_load_lds_dwordx4 v180, s[64:65]
	s_add_i32 m0, s35, 0x2000
	s_nop 0
	global_load_lds_dwordx4 v178, s[64:65]
	s_mov_b32 m0, s88
	s_nop 0
	global_load_lds_dwordx4 v180, s[98:99]
	s_mov_b32 m0, s89
	s_nop 0
	global_load_lds_dwordx4 v178, s[98:99]
	s_waitcnt vmcnt(8)
	s_waitcnt lgkmcnt(0)
	s_barrier
	s_setprio 1
	s_waitcnt lgkmcnt(0)
	v_mfma_f32_16x16x32_bf16 v[110:113], v[130:133], v[162:165], v[110:113]
	v_mfma_f32_16x16x32_bf16 v[106:109], v[138:141], v[162:165], v[106:109]
	v_mfma_f32_16x16x32_bf16 v[78:81], v[130:133], v[170:173], v[78:81]
	v_mfma_f32_16x16x32_bf16 v[74:77], v[138:141], v[170:173], v[74:77]
	v_mfma_f32_16x16x32_bf16 v[46:49], v[130:133], v[210:213], v[46:49]
	v_mfma_f32_16x16x32_bf16 v[42:45], v[138:141], v[210:213], v[42:45]
	v_mfma_f32_16x16x32_bf16 v[14:17], v[130:133], v[228:231], v[14:17]
	v_mfma_f32_16x16x32_bf16 v[10:13], v[138:141], v[228:231], v[10:13]
	v_mfma_f32_16x16x32_bf16 v[110:113], v[134:137], v[166:169], v[110:113]
	v_mfma_f32_16x16x32_bf16 v[106:109], v[142:145], v[166:169], v[106:109]
	v_mfma_f32_16x16x32_bf16 v[78:81], v[134:137], v[174:177], v[78:81]
	v_mfma_f32_16x16x32_bf16 v[74:77], v[142:145], v[174:177], v[74:77]
	v_mfma_f32_16x16x32_bf16 v[46:49], v[134:137], v[214:217], v[46:49]
	v_mfma_f32_16x16x32_bf16 v[42:45], v[142:145], v[214:217], v[42:45]
	v_mfma_f32_16x16x32_bf16 v[14:17], v[134:137], v[232:235], v[14:17]
	v_mfma_f32_16x16x32_bf16 v[10:13], v[142:145], v[232:235], v[10:13]
	s_setprio 0
	s_setprio 1
	v_mfma_f32_16x16x32_bf16 v[102:105], v[146:149], v[162:165], v[102:105]
	v_mfma_f32_16x16x32_bf16 v[98:101], v[154:157], v[162:165], v[98:101]
	v_mfma_f32_16x16x32_bf16 v[70:73], v[146:149], v[170:173], v[70:73]
	v_mfma_f32_16x16x32_bf16 v[66:69], v[154:157], v[170:173], v[66:69]
	v_mfma_f32_16x16x32_bf16 v[38:41], v[146:149], v[210:213], v[38:41]
	v_mfma_f32_16x16x32_bf16 v[34:37], v[154:157], v[210:213], v[34:37]
	v_mfma_f32_16x16x32_bf16 v[6:9], v[146:149], v[228:231], v[6:9]
	v_mfma_f32_16x16x32_bf16 v[2:5], v[154:157], v[228:231], v[2:5]
	v_mfma_f32_16x16x32_bf16 v[102:105], v[150:153], v[166:169], v[102:105]
	v_mfma_f32_16x16x32_bf16 v[98:101], v[158:161], v[166:169], v[98:101]
	v_mfma_f32_16x16x32_bf16 v[70:73], v[150:153], v[174:177], v[70:73]
	v_mfma_f32_16x16x32_bf16 v[66:69], v[158:161], v[174:177], v[66:69]
	v_mfma_f32_16x16x32_bf16 v[38:41], v[150:153], v[214:217], v[38:41]
	v_mfma_f32_16x16x32_bf16 v[34:37], v[158:161], v[214:217], v[34:37]
	v_mfma_f32_16x16x32_bf16 v[6:9], v[150:153], v[232:235], v[6:9]
	v_mfma_f32_16x16x32_bf16 v[2:5], v[158:161], v[232:235], v[2:5]
	s_setprio 0
	s_barrier
	s_add_i32 s33, s33, 2
	s_add_u32 s28, s28, 0x100
	s_addc_u32 s29, s29, 0
	s_add_u32 s62, s62, 0x100
	s_addc_u32 s63, s63, 0
	s_cmp_gt_u32 s33, 13
	s_cbranch_scc0 .LBB0_230
	s_and_b64 vcc, exec, s[48:49]
	s_cbranch_vccz .LBB0_233
	s_barrier

; #define PG8_STAGE(bufoff, gbase, voff) do { _Pragma("unroll") for (int _i = 0; _i < 2; ++_i) \
;         __builtin_amdgcn_global_load_lds((const unsigned*)((const char*)(gbase) + (voff)[_i]), (PG8_LAS unsigned*)(lds + (bufoff) + ldsw + _i * 8192), 16, 0, 0); } while (0)
; #define PG8_LDA(dst, b, h) do { _Pragma("unroll") for (int m = 0; m < 4; ++m) _Pragma("unroll") for (int k = 0; k < 2; ++k) dst[m][k] = *(const PG8_LAS bf16x8*)(lds + PG8_SA(b, h) + aoff + m * 2048 + k * 1024); } while (0)
; #define PG8_LDB(dst, b, h) do { _Pragma("unroll") for (int n = 0; n < 2; ++n) _Pragma("unroll") for (int k = 0; k < 2; ++k) dst[n][k] = *(const PG8_LAS bf16x8*)(lds + PG8_SB(b, h) + boff + n * 2048 + k * 1024); } while (0)
; #define PG8_SCHED __builtin_amdgcn_sched_barrier(0)
; template <class Epi, class Sched, bool ALIGN_EPI = false, bool SP2 = false>
; __device__ __forceinline__ void gemm_phase(PG8_LAS unsigned char* lds, const Gemm g, const Sched& S, const Epi& E) {
;     ...
;         const char* nA = has_next ? (const char*)g.A + (size_t)nxt.pm * tstep : cA; const char* nB = has_next ? (const char*)g.Bt + (size_t)nxt.pn * tstep : cB;
;         for (int t = 0; t < nt; t += 2) {
;             const bool last = (t == nt - 2);
;             const char* a1 = cA + (size_t)(t + 1) * kstep;
;             const char* a2 = last ? nA : cA + (size_t)(t + 2) * kstep; const char* b2 = last ? nB : cB + (size_t)(t + 2) * kstep;
;             const char* a3 = a2 + kstep; const char* b3 = b2 + kstep;
;             if (last && has_next) S.a_ready(nxt);
;             if constexpr (SP2) {
;             PG8_LDB(B0, 0, 0); PG8_LDB(B1, 0, 1); PG8_SCHED; PG8_LDA(At, 0, 0); PG8_STAGE(PG8_SA(1, 1), a1 + hstep, voffA);
;     ...
;         for (int a = 0; a < 2; ++a)
; #pragma unroll
;             for (int b = 0; b < 2; ++b)
; #pragma unroll
;                 for (int m = 0; m < 4; ++m)
; #pragma unroll
;                     for (int n = 0; n < 2; ++n) acc[a][b][m][n] = (f32x4){0.f, 0.f, 0.f, 0.f};
.LBB0_677:
	s_ashr_i32 s49, s48, 31
	s_lshl_b64 s[50:51], s[48:49], 19
	s_add_u32 s50, s2, s50
	s_addc_u32 s51, s3, s51
	s_and_b64 s[58:59], s[40:41], exec
	s_cselect_b32 s49, s51, s61
	s_cselect_b32 s75, s50, s60
	s_ashr_i32 s47, s46, 31
	s_lshl_b64 s[58:59], s[46:47], 19
	s_add_u32 s58, s14, s58
	s_addc_u32 s59, s15, s59
	s_and_b64 s[62:63], s[40:41], exec
	s_cselect_b32 s47, s59, s43
	s_cselect_b32 s76, s58, s42
	s_add_u32 s77, s42, 0x100
	s_addc_u32 s78, s43, 0
	s_add_u32 s42, s60, 0x40080
	v_mov_b32_e32 v2, 0
	s_addc_u32 s43, s61, 0
	s_mov_b32 s79, -2
	v_mov_b32_e32 v3, v2
	v_mov_b32_e32 v4, v2
	v_mov_b32_e32 v5, v2
	v_mov_b32_e32 v6, v2
	v_mov_b32_e32 v7, v2
	v_mov_b32_e32 v8, v2
	v_mov_b32_e32 v9, v2
	v_mov_b32_e32 v14, v2
	v_mov_b32_e32 v15, v2
	v_mov_b32_e32 v16, v2
	v_mov_b32_e32 v17, v2
	v_mov_b32_e32 v22, v2
	v_mov_b32_e32 v23, v2
	v_mov_b32_e32 v24, v2
	v_mov_b32_e32 v25, v2
	v_mov_b32_e32 v30, v2
	v_mov_b32_e32 v31, v2
	v_mov_b32_e32 v32, v2
	v_mov_b32_e32 v33, v2
	v_mov_b32_e32 v38, v2
	v_mov_b32_e32 v39, v2
	v_mov_b32_e32 v40, v2
	v_mov_b32_e32 v41, v2
	v_mov_b32_e32 v46, v2
	v_mov_b32_e32 v47, v2
	v_mov_b32_e32 v48, v2
	v_mov_b32_e32 v49, v2
	v_mov_b32_e32 v54, v2
	v_mov_b32_e32 v55, v2
	v_mov_b32_e32 v56, v2
	v_mov_b32_e32 v57, v2
	v_mov_b32_e32 v10, v2
	v_mov_b32_e32 v11, v2
	v_mov_b32_e32 v12, v2
	v_mov_b32_e32 v13, v2
	v_mov_b32_e32 v18, v2
	v_mov_b32_e32 v19, v2
	v_mov_b32_e32 v20, v2
	v_mov_b32_e32 v21, v2
	v_mov_b32_e32 v26, v2
	v_mov_b32_e32 v27, v2
	v_mov_b32_e32 v28, v2
	v_mov_b32_e32 v29, v2
	v_mov_b32_e32 v34, v2
	v_mov_b32_e32 v35, v2
	v_mov_b32_e32 v36, v2
	v_mov_b32_e32 v37, v2
	v_mov_b32_e32 v42, v2
	v_mov_b32_e32 v43, v2
	v_mov_b32_e32 v44, v2
	v_mov_b32_e32 v45, v2
	v_mov_b32_e32 v50, v2
	v_mov_b32_e32 v51, v2
	v_mov_b32_e32 v52, v2
	v_mov_b32_e32 v53, v2
	v_mov_b32_e32 v58, v2
	v_mov_b32_e32 v59, v2
	v_mov_b32_e32 v60, v2
	v_mov_b32_e32 v61, v2
	v_mov_b32_e32 v62, v2
	v_mov_b32_e32 v63, v2
	v_mov_b32_e32 v64, v2
	v_mov_b32_e32 v65, v2
	v_mov_b32_e32 v66, v2
	v_mov_b32_e32 v67, v2
	v_mov_b32_e32 v68, v2
	v_mov_b32_e32 v69, v2
	v_mov_b32_e32 v70, v2
	v_mov_b32_e32 v71, v2
	v_mov_b32_e32 v72, v2
	v_mov_b32_e32 v73, v2
	v_mov_b32_e32 v78, v2
	v_mov_b32_e32 v79, v2
	v_mov_b32_e32 v80, v2
	v_mov_b32_e32 v81, v2
	v_mov_b32_e32 v86, v2
	v_mov_b32_e32 v87, v2
	v_mov_b32_e32 v88, v2
	v_mov_b32_e32 v89, v2
	v_mov_b32_e32 v98, v2
	v_mov_b32_e32 v99, v2
	v_mov_b32_e32 v100, v2
	v_mov_b32_e32 v101, v2
	v_mov_b32_e32 v106, v2
	v_mov_b32_e32 v107, v2
	v_mov_b32_e32 v108, v2
	v_mov_b32_e32 v109, v2
	v_mov_b32_e32 v130, v2
	v_mov_b32_e32 v131, v2
	v_mov_b32_e32 v132, v2
	v_mov_b32_e32 v133, v2
	v_mov_b32_e32 v134, v2
	v_mov_b32_e32 v135, v2
	v_mov_b32_e32 v136, v2
	v_mov_b32_e32 v137, v2
	v_mov_b32_e32 v74, v2
	v_mov_b32_e32 v75, v2
	v_mov_b32_e32 v76, v2
	v_mov_b32_e32 v77, v2
	v_mov_b32_e32 v82, v2
	v_mov_b32_e32 v83, v2
	v_mov_b32_e32 v84, v2
	v_mov_b32_e32 v85, v2
	v_mov_b32_e32 v90, v2
	v_mov_b32_e32 v91, v2
	v_mov_b32_e32 v92, v2
	v_mov_b32_e32 v93, v2
	v_mov_b32_e32 v94, v2
	v_mov_b32_e32 v95, v2
	v_mov_b32_e32 v96, v2
	v_mov_b32_e32 v97, v2
	v_mov_b32_e32 v122, v2
	v_mov_b32_e32 v123, v2
	v_mov_b32_e32 v124, v2
	v_mov_b32_e32 v125, v2
	v_mov_b32_e32 v126, v2
	v_mov_b32_e32 v127, v2
	v_mov_b32_e32 v128, v2
	v_mov_b32_e32 v129, v2
	v_mov_b32_e32 v138, v2
	v_mov_b32_e32 v139, v2
	v_mov_b32_e32 v140, v2
	v_mov_b32_e32 v141, v2
	v_mov_b32_e32 v142, v2
	v_mov_b32_e32 v143, v2
	v_mov_b32_e32 v144, v2
	v_mov_b32_e32 v145, v2
	v_add_u32_e32 v249, 0x10000, v159
	v_add_u32_e32 v250, 0x14000, v159
	v_add_u32_e32 v251, 0x18000, v159
	v_add_u32_e32 v252, 0x1c000, v159
.LBB0_678:
	s_add_u32 s60, s42, 0xfffc0080
	s_addc_u32 s61, s43, -1
	s_add_i32 s80, 0, 0x10000
	s_cmp_eq_u32 s79, 12
	s_cselect_b32 s63, s49, s61
	s_cselect_b32 s62, s75, s60
	s_cselect_b32 s61, s47, s78
	s_cselect_b32 s60, s76, s77
	s_add_i32 s82, 0, 0x14000
	ds_read_b128 v[102:105], v249
	ds_read_b128 v[110:113], v249 offset:1024
	ds_read_b128 v[114:117], v249 offset:2048
	ds_read_b128 v[118:121], v249 offset:3072
	ds_read_b128 v[162:165], v250
	ds_read_b128 v[166:169], v250 offset:1024
	ds_read_b128 v[170:173], v250 offset:2048
	ds_read_b128 v[174:177], v250 offset:3072
	s_add_i32 m0, s28, 0xc000
	ds_read_b128 v[178:181], v161
	ds_read_b128 v[182:185], v161 offset:1024
	ds_read_b128 v[186:189], v161 offset:2048
	ds_read_b128 v[202:205], v161 offset:3072
	ds_read_b128 v[206:209], v161 offset:4096
	ds_read_b128 v[210:213], v161 offset:5120
	ds_read_b128 v[214:217], v161 offset:6144
	ds_read_b128 v[228:231], v161 offset:7168
	global_load_lds_dwordx4 v156, s[42:43]
	s_add_i32 m0, s28, 0xe000
	s_nop 0
	global_load_lds_dwordx4 v154, s[42:43]
	s_waitcnt vmcnt(8)
	s_waitcnt lgkmcnt(0)
	s_barrier
; #define PG8_STAGE(bufoff, gbase, voff) do { _Pragma("unroll") for (int _i = 0; _i < 2; ++_i) \
;         __builtin_amdgcn_global_load_lds((const unsigned*)((const char*)(gbase) + (voff)[_i]), (PG8_LAS unsigned*)(lds + (bufoff) + ldsw + _i * 8192), 16, 0, 0); } while (0)
; #define PG8_LDA(dst, b, h) do { _Pragma("unroll") for (int m = 0; m < 4; ++m) _Pragma("unroll") for (int k = 0; k < 2; ++k) dst[m][k] = *(const PG8_LAS bf16x8*)(lds + PG8_SA(b, h) + aoff + m * 2048 + k * 1024); } while (0)
; #define PG8_MMA(ai, bj, At, Bt) do { __builtin_amdgcn_s_setprio(1); _Pragma("unroll") for (int m = 0; m < 4; ++m) _Pragma("unroll") for (int n = 0; n < 2; ++n) _Pragma("unroll") for (int k = 0; k < 2; ++k) \
;         acc[ai][bj][m][n] = __builtin_amdgcn_mfma_f32_16x16x32_bf16(Bt[n][k], At[m][k], acc[ai][bj][m][n], 0, 0, 0); __builtin_amdgcn_s_setprio(0); } while (0)
; #define PG8_WAIT_V(n) asm volatile("s_waitcnt vmcnt(" #n ")" ::: "memory")
; #define PG8_WAIT_L(n) asm volatile("s_waitcnt lgkmcnt(" #n ")" ::: "memory")
; #define PG8_BAR __builtin_amdgcn_s_barrier()
; #define PG8_SCHED __builtin_amdgcn_sched_barrier(0)
; template <class Epi, class Sched, bool ALIGN_EPI = false, bool SP2 = false>
; __device__ __forceinline__ void gemm_phase(PG8_LAS unsigned char* lds, const Gemm g, const Sched& S, const Epi& E) {
;     ...
;             PG8_WAIT_V(8); PG8_WAIT_L(0); PG8_BAR; PG8_MMA(0, 0, At, B0); PG8_MMA(0, 1, At, B1); PG8_BAR; PG8_SCHED;
;             PG8_LDA(At, 0, 1); PG8_STAGE(PG8_SB(0, 0), b2, voffB); PG8_STAGE(PG8_SB(0, 1), b2 + hstep, voffB); PG8_STAGE(PG8_SA(0, 0), a2, voffA);
;             PG8_WAIT_V(8); PG8_WAIT_L(0); PG8_BAR; PG8_MMA(1, 0, At, B0); PG8_MMA(1, 1, At, B1); PG8_BAR; PG8_SCHED;
	s_setprio 1
	s_waitcnt lgkmcnt(0)
	v_mfma_f32_16x16x32_bf16 v[142:145], v[102:105], v[178:181], v[142:145]
	v_mfma_f32_16x16x32_bf16 v[138:141], v[114:117], v[178:181], v[138:141]
	v_mfma_f32_16x16x32_bf16 v[126:129], v[102:105], v[186:189], v[126:129]
	v_mfma_f32_16x16x32_bf16 v[122:125], v[114:117], v[186:189], v[122:125]
	v_mfma_f32_16x16x32_bf16 v[94:97], v[102:105], v[206:209], v[94:97]
	v_mfma_f32_16x16x32_bf16 v[90:93], v[114:117], v[206:209], v[90:93]
	v_mfma_f32_16x16x32_bf16 v[82:85], v[102:105], v[214:217], v[82:85]
	v_mfma_f32_16x16x32_bf16 v[74:77], v[114:117], v[214:217], v[74:77]
	v_mfma_f32_16x16x32_bf16 v[142:145], v[110:113], v[182:185], v[142:145]
	v_mfma_f32_16x16x32_bf16 v[138:141], v[118:121], v[182:185], v[138:141]
	v_mfma_f32_16x16x32_bf16 v[126:129], v[110:113], v[202:205], v[126:129]
	v_mfma_f32_16x16x32_bf16 v[122:125], v[118:121], v[202:205], v[122:125]
	v_mfma_f32_16x16x32_bf16 v[94:97], v[110:113], v[210:213], v[94:97]
	v_mfma_f32_16x16x32_bf16 v[90:93], v[118:121], v[210:213], v[90:93]
	v_mfma_f32_16x16x32_bf16 v[82:85], v[110:113], v[228:231], v[82:85]
	v_mfma_f32_16x16x32_bf16 v[74:77], v[118:121], v[228:231], v[74:77]
	s_setprio 0
	s_setprio 1
	v_mfma_f32_16x16x32_bf16 v[134:137], v[162:165], v[178:181], v[134:137]
	v_mfma_f32_16x16x32_bf16 v[130:133], v[170:173], v[178:181], v[130:133]
	v_mfma_f32_16x16x32_bf16 v[106:109], v[162:165], v[186:189], v[106:109]
	v_mfma_f32_16x16x32_bf16 v[98:101], v[170:173], v[186:189], v[98:101]
	v_mfma_f32_16x16x32_bf16 v[86:89], v[162:165], v[206:209], v[86:89]
	v_mfma_f32_16x16x32_bf16 v[78:81], v[170:173], v[206:209], v[78:81]
	v_mfma_f32_16x16x32_bf16 v[70:73], v[162:165], v[214:217], v[70:73]
	v_mfma_f32_16x16x32_bf16 v[66:69], v[170:173], v[214:217], v[66:69]
	v_mfma_f32_16x16x32_bf16 v[134:137], v[166:169], v[182:185], v[134:137]
	v_mfma_f32_16x16x32_bf16 v[130:133], v[174:177], v[182:185], v[130:133]
	v_mfma_f32_16x16x32_bf16 v[106:109], v[166:169], v[202:205], v[106:109]
	v_mfma_f32_16x16x32_bf16 v[98:101], v[174:177], v[202:205], v[98:101]
	v_mfma_f32_16x16x32_bf16 v[86:89], v[166:169], v[210:213], v[86:89]
	v_mfma_f32_16x16x32_bf16 v[78:81], v[174:177], v[210:213], v[78:81]
	v_mfma_f32_16x16x32_bf16 v[70:73], v[166:169], v[228:231], v[70:73]
	v_mfma_f32_16x16x32_bf16 v[66:69], v[174:177], v[228:231], v[66:69]
	s_setprio 0
	s_barrier
	s_add_i32 s80, s80, s20
	s_mov_b32 m0, s80
	ds_read_b128 v[178:181], v161 offset:16384
	ds_read_b128 v[182:185], v161 offset:17408
	ds_read_b128 v[186:189], v161 offset:18432
	ds_read_b128 v[202:205], v161 offset:19456
	ds_read_b128 v[206:209], v161 offset:20480
	ds_read_b128 v[210:213], v161 offset:21504
	ds_read_b128 v[214:217], v161 offset:22528
	ds_read_b128 v[228:231], v161 offset:23552
	global_load_lds_dwordx4 v150, s[60:61]
	s_add_i32 m0, s80, 0x2000
	s_add_u32 s80, s60, 0x40000
	s_addc_u32 s81, s61, 0
	s_add_i32 s82, s82, s20
	global_load_lds_dwordx4 v146, s[60:61]
	s_mov_b32 m0, s82
	s_nop 0
	global_load_lds_dwordx4 v150, s[80:81]
	s_add_i32 m0, s82, 0x2000
	s_nop 0
	global_load_lds_dwordx4 v146, s[80:81]
	s_mov_b32 m0, s28
	s_nop 0
	global_load_lds_dwordx4 v152, s[62:63]
	s_mov_b32 m0, s29
	s_nop 0
	global_load_lds_dwordx4 v148, s[62:63]
	s_waitcnt vmcnt(8)
	s_waitcnt lgkmcnt(0)
	s_barrier
	s_setprio 1
	s_waitcnt lgkmcnt(0)
	v_mfma_f32_16x16x32_bf16 v[62:65], v[102:105], v[178:181], v[62:65]
	v_mfma_f32_16x16x32_bf16 v[58:61], v[114:117], v[178:181], v[58:61]
	v_mfma_f32_16x16x32_bf16 v[50:53], v[102:105], v[186:189], v[50:53]
	v_mfma_f32_16x16x32_bf16 v[42:45], v[114:117], v[186:189], v[42:45]
	v_mfma_f32_16x16x32_bf16 v[34:37], v[102:105], v[206:209], v[34:37]
	v_mfma_f32_16x16x32_bf16 v[26:29], v[114:117], v[206:209], v[26:29]
	v_mfma_f32_16x16x32_bf16 v[18:21], v[102:105], v[214:217], v[18:21]
	v_mfma_f32_16x16x32_bf16 v[10:13], v[114:117], v[214:217], v[10:13]
	v_mfma_f32_16x16x32_bf16 v[62:65], v[110:113], v[182:185], v[62:65]
	v_mfma_f32_16x16x32_bf16 v[58:61], v[118:121], v[182:185], v[58:61]
	v_mfma_f32_16x16x32_bf16 v[50:53], v[110:113], v[202:205], v[50:53]
	v_mfma_f32_16x16x32_bf16 v[42:45], v[118:121], v[202:205], v[42:45]
	v_mfma_f32_16x16x32_bf16 v[34:37], v[110:113], v[210:213], v[34:37]
	v_mfma_f32_16x16x32_bf16 v[26:29], v[118:121], v[210:213], v[26:29]
	v_mfma_f32_16x16x32_bf16 v[18:21], v[110:113], v[228:231], v[18:21]
	v_mfma_f32_16x16x32_bf16 v[10:13], v[118:121], v[228:231], v[10:13]
	s_setprio 0
	s_setprio 1
	v_mfma_f32_16x16x32_bf16 v[54:57], v[162:165], v[178:181], v[54:57]
	v_mfma_f32_16x16x32_bf16 v[46:49], v[170:173], v[178:181], v[46:49]
	v_mfma_f32_16x16x32_bf16 v[38:41], v[162:165], v[186:189], v[38:41]
	v_mfma_f32_16x16x32_bf16 v[30:33], v[170:173], v[186:189], v[30:33]
	v_mfma_f32_16x16x32_bf16 v[22:25], v[162:165], v[206:209], v[22:25]
	v_mfma_f32_16x16x32_bf16 v[14:17], v[170:173], v[206:209], v[14:17]
	v_mfma_f32_16x16x32_bf16 v[6:9], v[162:165], v[214:217], v[6:9]
	v_mfma_f32_16x16x32_bf16 v[2:5], v[170:173], v[214:217], v[2:5]
	v_mfma_f32_16x16x32_bf16 v[54:57], v[166:169], v[182:185], v[54:57]
	v_mfma_f32_16x16x32_bf16 v[46:49], v[174:177], v[182:185], v[46:49]
	v_mfma_f32_16x16x32_bf16 v[38:41], v[166:169], v[202:205], v[38:41]
	v_mfma_f32_16x16x32_bf16 v[30:33], v[174:177], v[202:205], v[30:33]
	v_mfma_f32_16x16x32_bf16 v[22:25], v[166:169], v[210:213], v[22:25]
	v_mfma_f32_16x16x32_bf16 v[14:17], v[174:177], v[210:213], v[14:17]
	v_mfma_f32_16x16x32_bf16 v[6:9], v[166:169], v[228:231], v[6:9]
	v_mfma_f32_16x16x32_bf16 v[2:5], v[174:177], v[228:231], v[2:5]
	s_setprio 0
	s_barrier
; #define PG8_STAGE(bufoff, gbase, voff) do { _Pragma("unroll") for (int _i = 0; _i < 2; ++_i) \
;         __builtin_amdgcn_global_load_lds((const unsigned*)((const char*)(gbase) + (voff)[_i]), (PG8_LAS unsigned*)(lds + (bufoff) + ldsw + _i * 8192), 16, 0, 0); } while (0)
; #define PG8_LDA(dst, b, h) do { _Pragma("unroll") for (int m = 0; m < 4; ++m) _Pragma("unroll") for (int k = 0; k < 2; ++k) dst[m][k] = *(const PG8_LAS bf16x8*)(lds + PG8_SA(b, h) + aoff + m * 2048 + k * 1024); } while (0)
; #define PG8_LDB(dst, b, h) do { _Pragma("unroll") for (int n = 0; n < 2; ++n) _Pragma("unroll") for (int k = 0; k < 2; ++k) dst[n][k] = *(const PG8_LAS bf16x8*)(lds + PG8_SB(b, h) + boff + n * 2048 + k * 1024); } while (0)
; #define PG8_MMA(ai, bj, At, Bt) do { __builtin_amdgcn_s_setprio(1); _Pragma("unroll") for (int m = 0; m < 4; ++m) _Pragma("unroll") for (int n = 0; n < 2; ++n) _Pragma("unroll") for (int k = 0; k < 2; ++k) \
;         acc[ai][bj][m][n] = __builtin_amdgcn_mfma_f32_16x16x32_bf16(Bt[n][k], At[m][k], acc[ai][bj][m][n], 0, 0, 0); __builtin_amdgcn_s_setprio(0); } while (0)
; #define PG8_WAIT_V(n) asm volatile("s_waitcnt vmcnt(" #n ")" ::: "memory")
; #define PG8_WAIT_L(n) asm volatile("s_waitcnt lgkmcnt(" #n ")" ::: "memory")
; #define PG8_BAR __builtin_amdgcn_s_barrier()
; #define PG8_SCHED __builtin_amdgcn_sched_barrier(0)
; template <class Epi, class Sched, bool ALIGN_EPI = false, bool SP2 = false>
; __device__ __forceinline__ void gemm_phase(PG8_LAS unsigned char* lds, const Gemm g, const Sched& S, const Epi& E) {
;     ...
;             PG8_LDB(B0, 1, 0); PG8_LDB(B1, 1, 1); PG8_SCHED; PG8_LDA(At, 1, 0); PG8_STAGE(PG8_SA(0, 1), a2 + hstep, voffA);
;             PG8_WAIT_V(8); PG8_WAIT_L(0); PG8_BAR; PG8_MMA(0, 0, At, B0); PG8_MMA(0, 1, At, B1); PG8_BAR; PG8_SCHED;
;             PG8_LDA(At, 1, 1); PG8_STAGE(PG8_SB(1, 0), b3, voffB); PG8_STAGE(PG8_SB(1, 1), b3 + hstep, voffB); PG8_STAGE(PG8_SA(1, 0), a3, voffA);
;             PG8_WAIT_V(8); PG8_WAIT_L(0); PG8_BAR; PG8_MMA(1, 0, At, B0); PG8_MMA(1, 1, At, B1); PG8_BAR; PG8_SCHED;
;     ...
;         if constexpr (ALIGN_EPI) { if (wr == 0) PG8_BAR; }
	s_add_i32 s80, 0, 0x18000
	s_add_i32 s81, 0, 0x1c000
	ds_read_b128 v[102:105], v251
	ds_read_b128 v[110:113], v251 offset:1024
	ds_read_b128 v[114:117], v251 offset:2048
	ds_read_b128 v[118:121], v251 offset:3072
	ds_read_b128 v[162:165], v252
	ds_read_b128 v[166:169], v252 offset:1024
	ds_read_b128 v[170:173], v252 offset:2048
	ds_read_b128 v[174:177], v252 offset:3072
	s_add_u32 s62, s62, 0x40000
	s_addc_u32 s63, s63, 0
	s_add_u32 s98, s62, 0xfffc0080
	s_addc_u32 s99, s63, -1
	s_mov_b32 m0, s33
	ds_read_b128 v[178:181], v161 offset:32768
	ds_read_b128 v[182:185], v161 offset:33792
	ds_read_b128 v[186:189], v161 offset:34816
	ds_read_b128 v[202:205], v161 offset:35840
	ds_read_b128 v[206:209], v161 offset:36864
	ds_read_b128 v[210:213], v161 offset:37888
	ds_read_b128 v[214:217], v161 offset:38912
	ds_read_b128 v[228:231], v161 offset:39936
	global_load_lds_dwordx4 v152, s[62:63]
	s_mov_b32 m0, s64
	s_nop 0
	global_load_lds_dwordx4 v148, s[62:63]
	s_waitcnt vmcnt(8)
	s_waitcnt lgkmcnt(0)
	s_barrier
	s_setprio 1
	s_waitcnt lgkmcnt(0)
	v_mfma_f32_16x16x32_bf16 v[142:145], v[102:105], v[178:181], v[142:145]
	v_mfma_f32_16x16x32_bf16 v[138:141], v[114:117], v[178:181], v[138:141]
	v_mfma_f32_16x16x32_bf16 v[126:129], v[102:105], v[186:189], v[126:129]
	v_mfma_f32_16x16x32_bf16 v[122:125], v[114:117], v[186:189], v[122:125]
	v_mfma_f32_16x16x32_bf16 v[94:97], v[102:105], v[206:209], v[94:97]
	v_mfma_f32_16x16x32_bf16 v[90:93], v[114:117], v[206:209], v[90:93]
	v_mfma_f32_16x16x32_bf16 v[82:85], v[102:105], v[214:217], v[82:85]
	v_mfma_f32_16x16x32_bf16 v[74:77], v[114:117], v[214:217], v[74:77]
	v_mfma_f32_16x16x32_bf16 v[142:145], v[110:113], v[182:185], v[142:145]
	v_mfma_f32_16x16x32_bf16 v[138:141], v[118:121], v[182:185], v[138:141]
	v_mfma_f32_16x16x32_bf16 v[126:129], v[110:113], v[202:205], v[126:129]
	v_mfma_f32_16x16x32_bf16 v[122:125], v[118:121], v[202:205], v[122:125]
	v_mfma_f32_16x16x32_bf16 v[94:97], v[110:113], v[210:213], v[94:97]
	v_mfma_f32_16x16x32_bf16 v[90:93], v[118:121], v[210:213], v[90:93]
	v_mfma_f32_16x16x32_bf16 v[82:85], v[110:113], v[228:231], v[82:85]
	v_mfma_f32_16x16x32_bf16 v[74:77], v[118:121], v[228:231], v[74:77]
	s_setprio 0
	s_setprio 1
	v_mfma_f32_16x16x32_bf16 v[134:137], v[162:165], v[178:181], v[134:137]
	v_mfma_f32_16x16x32_bf16 v[130:133], v[170:173], v[178:181], v[130:133]
	v_mfma_f32_16x16x32_bf16 v[106:109], v[162:165], v[186:189], v[106:109]
	v_mfma_f32_16x16x32_bf16 v[98:101], v[170:173], v[186:189], v[98:101]
	v_mfma_f32_16x16x32_bf16 v[86:89], v[162:165], v[206:209], v[86:89]
	v_mfma_f32_16x16x32_bf16 v[78:81], v[170:173], v[206:209], v[78:81]
	v_mfma_f32_16x16x32_bf16 v[70:73], v[162:165], v[214:217], v[70:73]
	v_mfma_f32_16x16x32_bf16 v[66:69], v[170:173], v[214:217], v[66:69]
	v_mfma_f32_16x16x32_bf16 v[134:137], v[166:169], v[182:185], v[134:137]
	v_mfma_f32_16x16x32_bf16 v[130:133], v[174:177], v[182:185], v[130:133]
	v_mfma_f32_16x16x32_bf16 v[106:109], v[166:169], v[202:205], v[106:109]
	v_mfma_f32_16x16x32_bf16 v[98:101], v[174:177], v[202:205], v[98:101]
	v_mfma_f32_16x16x32_bf16 v[86:89], v[166:169], v[210:213], v[86:89]
	v_mfma_f32_16x16x32_bf16 v[78:81], v[174:177], v[210:213], v[78:81]
	v_mfma_f32_16x16x32_bf16 v[70:73], v[166:169], v[228:231], v[70:73]
	v_mfma_f32_16x16x32_bf16 v[66:69], v[174:177], v[228:231], v[66:69]
	s_setprio 0
	s_barrier
	s_add_i32 s62, s80, s20
	s_add_u32 s60, s60, s38
	s_addc_u32 s61, s61, s39
	s_mov_b32 m0, s62
	ds_read_b128 v[178:181], v161 offset:49152
	ds_read_b128 v[182:185], v161 offset:50176
	ds_read_b128 v[186:189], v161 offset:51200
	ds_read_b128 v[202:205], v161 offset:52224
	ds_read_b128 v[206:209], v161 offset:53248
	ds_read_b128 v[210:213], v161 offset:54272
	ds_read_b128 v[214:217], v161 offset:55296
	ds_read_b128 v[228:231], v161 offset:56320
	global_load_lds_dwordx4 v150, s[60:61]
	s_add_i32 m0, s62, 0x2000
	s_add_i32 s62, s81, s20
	global_load_lds_dwordx4 v146, s[60:61]
	s_add_u32 s60, s60, 0x40000
	s_addc_u32 s61, s61, 0
	s_mov_b32 m0, s62
	s_nop 0
	global_load_lds_dwordx4 v150, s[60:61]
	s_add_i32 m0, s62, 0x2000
	s_nop 0
	global_load_lds_dwordx4 v146, s[60:61]
	s_mov_b32 m0, s69
	s_nop 0
	global_load_lds_dwordx4 v152, s[98:99]
	s_mov_b32 m0, s70
	s_nop 0
	global_load_lds_dwordx4 v148, s[98:99]
	s_waitcnt vmcnt(8)
	s_waitcnt lgkmcnt(0)
	s_barrier
	s_setprio 1
	s_waitcnt lgkmcnt(0)
	v_mfma_f32_16x16x32_bf16 v[62:65], v[102:105], v[178:181], v[62:65]
	v_mfma_f32_16x16x32_bf16 v[58:61], v[114:117], v[178:181], v[58:61]
	v_mfma_f32_16x16x32_bf16 v[50:53], v[102:105], v[186:189], v[50:53]
	v_mfma_f32_16x16x32_bf16 v[42:45], v[114:117], v[186:189], v[42:45]
	v_mfma_f32_16x16x32_bf16 v[34:37], v[102:105], v[206:209], v[34:37]
	v_mfma_f32_16x16x32_bf16 v[26:29], v[114:117], v[206:209], v[26:29]
	v_mfma_f32_16x16x32_bf16 v[18:21], v[102:105], v[214:217], v[18:21]
	v_mfma_f32_16x16x32_bf16 v[10:13], v[114:117], v[214:217], v[10:13]
	v_mfma_f32_16x16x32_bf16 v[62:65], v[110:113], v[182:185], v[62:65]
	v_mfma_f32_16x16x32_bf16 v[58:61], v[118:121], v[182:185], v[58:61]
	v_mfma_f32_16x16x32_bf16 v[50:53], v[110:113], v[202:205], v[50:53]
	v_mfma_f32_16x16x32_bf16 v[42:45], v[118:121], v[202:205], v[42:45]
	v_mfma_f32_16x16x32_bf16 v[34:37], v[110:113], v[210:213], v[34:37]
	v_mfma_f32_16x16x32_bf16 v[26:29], v[118:121], v[210:213], v[26:29]
	v_mfma_f32_16x16x32_bf16 v[18:21], v[110:113], v[228:231], v[18:21]
	v_mfma_f32_16x16x32_bf16 v[10:13], v[118:121], v[228:231], v[10:13]
	s_setprio 0
	s_setprio 1
	v_mfma_f32_16x16x32_bf16 v[54:57], v[162:165], v[178:181], v[54:57]
	v_mfma_f32_16x16x32_bf16 v[46:49], v[170:173], v[178:181], v[46:49]
	v_mfma_f32_16x16x32_bf16 v[38:41], v[162:165], v[186:189], v[38:41]
	v_mfma_f32_16x16x32_bf16 v[30:33], v[170:173], v[186:189], v[30:33]
	v_mfma_f32_16x16x32_bf16 v[22:25], v[162:165], v[206:209], v[22:25]
	v_mfma_f32_16x16x32_bf16 v[14:17], v[170:173], v[206:209], v[14:17]
	v_mfma_f32_16x16x32_bf16 v[6:9], v[162:165], v[214:217], v[6:9]
	v_mfma_f32_16x16x32_bf16 v[2:5], v[170:173], v[214:217], v[2:5]
	v_mfma_f32_16x16x32_bf16 v[54:57], v[166:169], v[182:185], v[54:57]
	v_mfma_f32_16x16x32_bf16 v[46:49], v[174:177], v[182:185], v[46:49]
	v_mfma_f32_16x16x32_bf16 v[38:41], v[166:169], v[202:205], v[38:41]
	v_mfma_f32_16x16x32_bf16 v[30:33], v[174:177], v[202:205], v[30:33]
	v_mfma_f32_16x16x32_bf16 v[22:25], v[166:169], v[210:213], v[22:25]
	v_mfma_f32_16x16x32_bf16 v[14:17], v[174:177], v[210:213], v[14:17]
	v_mfma_f32_16x16x32_bf16 v[6:9], v[166:169], v[228:231], v[6:9]
	v_mfma_f32_16x16x32_bf16 v[2:5], v[174:177], v[228:231], v[2:5]
	s_setprio 0
	s_barrier
	s_add_i32 s79, s79, 2
	s_add_u32 s77, s77, 0x100
	s_addc_u32 s78, s78, 0
	s_add_u32 s42, s42, 0x100
	s_addc_u32 s43, s43, 0
	s_cmp_gt_u32 s79, 13
	s_cbranch_scc0 .LBB0_678
	s_and_b64 vcc, exec, s[44:45]
	s_movk_i32 s75, 0x1000
	s_cbranch_vccz .LBB0_681
	s_barrier

; __global__ void __launch_bounds__(NTHR, 2) hymba_fwd(Params Pk) {
	.amdhsa_kernel _Z9hymba_fwd6Params
		.amdhsa_group_segment_fixed_size 0
		.amdhsa_private_segment_fixed_size 0
		.amdhsa_kernarg_size 560
		.amdhsa_user_sgpr_count 2
		.amdhsa_user_sgpr_dispatch_ptr 0
		.amdhsa_user_sgpr_queue_ptr 0
		.amdhsa_user_sgpr_kernarg_segment_ptr 1
		.amdhsa_user_sgpr_dispatch_id 0
		.amdhsa_user_sgpr_kernarg_preload_length 0
		.amdhsa_user_sgpr_kernarg_preload_offset 0
		.amdhsa_user_sgpr_private_segment_size 0
		.amdhsa_uses_dynamic_stack 0
		.amdhsa_enable_private_segment 0
		.amdhsa_system_sgpr_workgroup_id_x 1
		.amdhsa_system_sgpr_workgroup_id_y 0
		.amdhsa_system_sgpr_workgroup_id_z 0
		.amdhsa_system_sgpr_workgroup_info 0
		.amdhsa_system_vgpr_workitem_id 2
		.amdhsa_next_free_vgpr 253
		.amdhsa_next_free_sgpr 100
		.amdhsa_accum_offset 256
		.amdhsa_reserve_vcc 1
		.amdhsa_float_round_mode_32 0
		.amdhsa_float_round_mode_16_64 0
		.amdhsa_float_denorm_mode_32 3
		.amdhsa_float_denorm_mode_16_64 3
		.amdhsa_dx10_clamp 1
		.amdhsa_ieee_mode 1
		.amdhsa_fp16_overflow 0
		.amdhsa_tg_split 0
		.amdhsa_exception_fp_ieee_invalid_op 0
		.amdhsa_exception_fp_denorm_src 0
		.amdhsa_exception_fp_ieee_div_zero 0
		.amdhsa_exception_fp_ieee_overflow 0
		.amdhsa_exception_fp_ieee_underflow 0
		.amdhsa_exception_fp_ieee_inexact 0
		.amdhsa_exception_int_div_zero 0
	.end_amdhsa_kernel

; __global__ void __launch_bounds__(NTHR, 2) hymba_fwd(Params Pk) {
amdhsa.kernels:
  - .agpr_count:     0
    .args:
      - .offset:         0
        .size:           304
        .value_kind:     by_value
      - .offset:         304
        .size:           4
        .value_kind:     hidden_block_count_x
      - .offset:         308
        .size:           4
        .value_kind:     hidden_block_count_y
      - .offset:         312
        .size:           4
        .value_kind:     hidden_block_count_z
      - .offset:         316
        .size:           2
        .value_kind:     hidden_group_size_x
      - .offset:         318
        .size:           2
        .value_kind:     hidden_group_size_y
      - .offset:         320
        .size:           2
        .value_kind:     hidden_group_size_z
      - .offset:         322
        .size:           2
        .value_kind:     hidden_remainder_x
      - .offset:         324
        .size:           2
        .value_kind:     hidden_remainder_y
      - .offset:         326
        .size:           2
        .value_kind:     hidden_remainder_z
      - .offset:         344
        .size:           8
        .value_kind:     hidden_global_offset_x
      - .offset:         352
        .size:           8
        .value_kind:     hidden_global_offset_y
      - .offset:         360
        .size:           8
        .value_kind:     hidden_global_offset_z
      - .offset:         368
        .size:           2
        .value_kind:     hidden_grid_dims
      - .offset:         392
        .size:           8
        .value_kind:     hidden_multigrid_sync_arg
      - .offset:         424
        .size:           4
        .value_kind:     hidden_dynamic_lds_size
    .group_segment_fixed_size: 0
    .kernarg_segment_align: 8
    .kernarg_segment_size: 560
    .language:       OpenCL C
    .language_version:
      - 2
      - 0
    .max_flat_workgroup_size: 512
    .name:           _Z9hymba_fwd6Params
    .private_segment_fixed_size: 0
    .sgpr_count:     106
    .sgpr_spill_count: 152
    .symbol:         _Z9hymba_fwd6Params.kd
    .uniform_work_group_size: 1
    .uses_dynamic_stack: false
    .vgpr_count:     253
    .vgpr_spill_count: 0
    .wavefront_size: 64
